# re-measure of v129 (epilogue gain vectors loaded up front)
# speedup vs baseline: 1.0062x; 1.0005x over previous
; template <int DV, int NMAP> ...
;     ...
;         if (mp == 0) {
;             float ss[2] = {0.f, 0.f};
; #pragma unroll
;             for (int db = 0; db < DV / 16; ++db)
; #pragma unroll
;                 for (int qb = 0; qb < 2; ++qb) { const f32x4 x = o[db][qb] * inv[qb] - xch[(db * 2 + qb) * 64 + lane]; o[db][qb] = x; ss[qb] += (x[0] * x[0] + x[1] * x[1]) + (x[2] * x[2] + x[3] * x[3]); if (qb == 1 && (db & 1)) asm volatile("" ::: "memory"); }
; #pragma unroll
;             for (int qb = 0; qb < 2; ++qb) { float v = ss[qb]; v += __shfl_xor(v, 16); v += __shfl_xor(v, 32); ss[qb] = outscale / sqrtf(v * (1.0f / DV) + RMS_EPS); }
; #pragma unroll
;             for (int db = 0; db < DV / 16; ++db) { const f32x4 g = *(const f32x4*)(subg + 16 * db + 4 * fq);
.LBB0_329:
	s_waitcnt lgkmcnt(0)
	s_barrier
	s_cmpk_gt_u32 s20, 0xff
	v_mov_b64_e32 v[238:239], v[214:215]
	s_cbranch_scc1 .LBB0_297
	v_lshlrev_b32_e32 v206, 4, v236
	global_load_dwordx4 v[160:163], v206, s[46:47]
	global_load_dwordx4 v[164:167], v206, s[46:47] offset:64
	global_load_dwordx4 v[168:171], v206, s[46:47] offset:128
	global_load_dwordx4 v[172:175], v206, s[46:47] offset:192
	global_load_dwordx4 v[176:179], v206, s[46:47] offset:256
	global_load_dwordx4 v[180:183], v206, s[46:47] offset:320
	global_load_dwordx4 v[184:187], v206, s[46:47] offset:384
	global_load_dwordx4 v[188:191], v206, s[46:47] offset:448
	global_load_dwordx4 v[192:195], v206, s[46:47] offset:512
	global_load_dwordx4 v[196:199], v206, s[46:47] offset:576
	global_load_dwordx4 v[200:203], v206, s[46:47] offset:640
	global_load_dwordx4 v[148:151], v206, s[46:47] offset:704
	global_load_dwordx4 v[152:155], v206, s[46:47] offset:768
	global_load_dwordx4 v[240:243], v206, s[46:47] offset:832
	global_load_dwordx4 v[244:247], v206, s[46:47] offset:896
	global_load_dwordx4 v[248:251], v206, s[46:47] offset:960
	ds_read_b128 v[132:135], v129
	v_lshlrev_b32_e32 v204, 3, v236
	s_waitcnt lgkmcnt(0)
	v_xor_b32_e32 v125, 0x80000000, v135
	v_xor_b32_e32 v124, 0x80000000, v134
	v_pk_fma_f32 v[124:125], v[158:159], v[130:131], v[124:125] op_sel_hi:[1,0,1]
	v_pk_fma_f32 v[126:127], v[156:157], v[130:131], v[132:133] op_sel_hi:[1,0,1] neg_lo:[0,0,1] neg_hi:[0,0,1]
	v_pk_mul_f32 v[132:133], v[124:125], v[124:125]
	v_pk_mul_f32 v[134:135], v[126:127], v[126:127]
	s_nop 0
	v_pk_mov_b32 v[136:137], v[134:135], v[132:133] op_sel:[1,0]
	v_mov_b32_e32 v135, v133
	v_pk_add_f32 v[132:133], v[136:137], v[134:135]
	ds_read_b128 v[134:137], v129 offset:1024
	v_pk_add_f32 v[132:133], v[132:133], v[132:133] op_sel:[0,1] op_sel_hi:[1,0]
	s_waitcnt lgkmcnt(0)
	v_xor_b32_e32 v137, 0x80000000, v137
	v_xor_b32_e32 v136, 0x80000000, v136
	v_pk_fma_f32 v[122:123], v[122:123], v[128:129], v[136:137] op_sel_hi:[1,0,1]
	v_pk_fma_f32 v[120:121], v[120:121], v[128:129], v[134:135] op_sel_hi:[1,0,1] neg_lo:[0,0,1] neg_hi:[0,0,1]
	v_pk_mul_f32 v[134:135], v[122:123], v[122:123]
	v_pk_mul_f32 v[136:137], v[120:121], v[120:121]
	s_nop 0
	v_pk_mov_b32 v[138:139], v[136:137], v[134:135] op_sel:[1,0]
	v_mov_b32_e32 v137, v135
	v_pk_add_f32 v[134:135], v[138:139], v[136:137]
	ds_read_b128 v[136:139], v129 offset:2048
	v_pk_add_f32 v[134:135], v[134:135], v[134:135] op_sel:[0,1] op_sel_hi:[1,0]
	s_waitcnt lgkmcnt(0)
	v_xor_b32_e32 v139, 0x80000000, v139
	v_xor_b32_e32 v138, 0x80000000, v138
	v_pk_fma_f32 v[118:119], v[118:119], v[130:131], v[138:139] op_sel_hi:[1,0,1]
	v_pk_fma_f32 v[116:117], v[116:117], v[130:131], v[136:137] op_sel_hi:[1,0,1] neg_lo:[0,0,1] neg_hi:[0,0,1]
	v_pk_mul_f32 v[136:137], v[118:119], v[118:119]
	v_pk_mul_f32 v[138:139], v[116:117], v[116:117]
	s_nop 0
	v_pk_mov_b32 v[140:141], v[138:139], v[136:137] op_sel:[1,0]
	v_mov_b32_e32 v139, v137
	v_pk_add_f32 v[142:143], v[140:141], v[138:139]
	ds_read_b128 v[136:139], v129 offset:3072
	s_waitcnt lgkmcnt(0)
	v_xor_b32_e32 v139, 0x80000000, v139
	v_xor_b32_e32 v138, 0x80000000, v138
	v_pk_fma_f32 v[114:115], v[114:115], v[128:129], v[138:139] op_sel_hi:[1,0,1]
	v_pk_fma_f32 v[112:113], v[112:113], v[128:129], v[136:137] op_sel_hi:[1,0,1] neg_lo:[0,0,1] neg_hi:[0,0,1]
	v_pk_mul_f32 v[136:137], v[114:115], v[114:115]
	v_pk_mul_f32 v[138:139], v[112:113], v[112:113]
	s_nop 0
	v_pk_mov_b32 v[140:141], v[138:139], v[136:137] op_sel:[1,0]
	v_mov_b32_e32 v139, v137
	v_pk_add_f32 v[136:137], v[140:141], v[138:139]
	ds_read_b128 v[138:141], v129 offset:4096
	v_pk_add_f32 v[136:137], v[136:137], v[136:137] op_sel:[0,1] op_sel_hi:[1,0]
	s_waitcnt lgkmcnt(0)
	v_xor_b32_e32 v141, 0x80000000, v141
	v_xor_b32_e32 v140, 0x80000000, v140
	v_pk_fma_f32 v[110:111], v[110:111], v[130:131], v[140:141] op_sel_hi:[1,0,1]
	v_pk_fma_f32 v[108:109], v[108:109], v[130:131], v[138:139] op_sel_hi:[1,0,1] neg_lo:[0,0,1] neg_hi:[0,0,1]
	ds_read_b128 v[138:141], v129 offset:5120
	s_waitcnt lgkmcnt(0)
	v_xor_b32_e32 v141, 0x80000000, v141
	v_xor_b32_e32 v140, 0x80000000, v140
	v_pk_fma_f32 v[106:107], v[106:107], v[128:129], v[140:141] op_sel_hi:[1,0,1]
	v_pk_fma_f32 v[104:105], v[104:105], v[128:129], v[138:139] op_sel_hi:[1,0,1] neg_lo:[0,0,1] neg_hi:[0,0,1]
	ds_read_b128 v[138:141], v129 offset:6144
	s_waitcnt lgkmcnt(0)
	v_xor_b32_e32 v141, 0x80000000, v141
	v_xor_b32_e32 v140, 0x80000000, v140
	v_pk_fma_f32 v[100:101], v[100:101], v[130:131], v[138:139] op_sel_hi:[1,0,1] neg_lo:[0,0,1] neg_hi:[0,0,1]
	v_pk_fma_f32 v[102:103], v[102:103], v[130:131], v[140:141] op_sel_hi:[1,0,1]
	v_mul_f32_e32 v131, v100, v100
	v_mul_f32_e32 v140, v101, v101
	v_pk_add_f32 v[138:139], v[142:143], v[142:143] op_sel:[0,1] op_sel_hi:[1,0]
	v_mov_b32_e32 v133, v131
	v_mov_b32_e32 v139, v140
	v_pk_add_f32 v[132:133], v[132:133], v[138:139]
	v_mul_f32_e32 v138, v109, v109
	v_mul_f32_e32 v141, v102, v102
	v_pk_fma_f32 v[138:139], v[108:109], v[108:109], v[138:139] op_sel_hi:[1,1,0]
	v_mul_f32_e32 v140, v111, v111
	v_mul_f32_e32 v144, v103, v103
	v_mov_b32_e32 v139, v141
	v_pk_fma_f32 v[140:141], v[110:111], v[110:111], v[140:141] op_sel_hi:[1,1,0]
	s_nop 0
	v_mov_b32_e32 v141, v144
	v_pk_add_f32 v[138:139], v[138:139], v[140:141]
	s_nop 0
	v_pk_add_f32 v[132:133], v[132:133], v[138:139]
	ds_read_b128 v[138:141], v129 offset:7168
	v_pk_add_f32 v[132:133], v[132:133], v[132:133] op_sel:[0,1] op_sel_hi:[1,0]
	s_waitcnt lgkmcnt(0)
; template <int DV, int NMAP> ...
;     ...
;                 for (int qb = 0; qb < 2; ++qb) { const f32x4 x = o[db][qb] * inv[qb] - xch[(db * 2 + qb) * 64 + lane]; o[db][qb] = x; ss[qb] += (x[0] * x[0] + x[1] * x[1]) + (x[2] * x[2] + x[3] * x[3]); if (qb == 1 && (db & 1)) asm volatile("" ::: "memory"); }
	v_pk_fma_f32 v[96:97], v[96:97], v[128:129], v[138:139] op_sel_hi:[1,0,1] neg_lo:[0,0,1] neg_hi:[0,0,1]
	s_nop 0
	v_mul_f32_e32 v131, v96, v96
	v_mul_f32_e32 v138, v97, v97
	v_xor_b32_e32 v141, 0x80000000, v141
	v_xor_b32_e32 v140, 0x80000000, v140
	v_mov_b32_e32 v135, v131
	v_mov_b32_e32 v137, v138
	v_pk_fma_f32 v[98:99], v[98:99], v[128:129], v[140:141] op_sel_hi:[1,0,1]
	v_pk_add_f32 v[134:135], v[134:135], v[136:137]
	v_mul_f32_e32 v136, v105, v105
	v_mul_f32_e32 v139, v98, v98
	v_pk_fma_f32 v[136:137], v[104:105], v[104:105], v[136:137] op_sel_hi:[1,1,0]
	v_mul_f32_e32 v138, v107, v107
	v_mul_f32_e32 v140, v99, v99
	v_mov_b32_e32 v137, v139
	v_pk_fma_f32 v[138:139], v[106:107], v[106:107], v[138:139] op_sel_hi:[1,1,0]
	s_nop 0
	v_mov_b32_e32 v139, v140
	v_pk_add_f32 v[136:137], v[136:137], v[138:139]
	s_nop 0
	v_pk_add_f32 v[134:135], v[134:135], v[136:137]
	ds_read_b128 v[136:139], v129 offset:8192
	v_pk_add_f32 v[134:135], v[134:135], v[134:135] op_sel:[0,1] op_sel_hi:[1,0]
	s_waitcnt lgkmcnt(0)
	v_xor_b32_e32 v139, 0x80000000, v139
	v_xor_b32_e32 v138, 0x80000000, v138
	v_pk_fma_f32 v[94:95], v[94:95], v[130:131], v[138:139] op_sel_hi:[1,0,1]
	v_pk_fma_f32 v[92:93], v[92:93], v[130:131], v[136:137] op_sel_hi:[1,0,1] neg_lo:[0,0,1] neg_hi:[0,0,1]
	v_pk_mul_f32 v[136:137], v[94:95], v[94:95]
	v_pk_mul_f32 v[138:139], v[92:93], v[92:93]
	s_nop 0
	v_pk_mov_b32 v[140:141], v[138:139], v[136:137] op_sel:[1,0]
	v_mov_b32_e32 v139, v137
	v_pk_add_f32 v[142:143], v[140:141], v[138:139]
	ds_read_b128 v[136:139], v129 offset:9216
	s_waitcnt lgkmcnt(0)
	v_xor_b32_e32 v139, 0x80000000, v139
	v_xor_b32_e32 v138, 0x80000000, v138
	v_pk_fma_f32 v[90:91], v[90:91], v[128:129], v[138:139] op_sel_hi:[1,0,1]
	v_pk_fma_f32 v[88:89], v[88:89], v[128:129], v[136:137] op_sel_hi:[1,0,1] neg_lo:[0,0,1] neg_hi:[0,0,1]
	v_pk_mul_f32 v[136:137], v[90:91], v[90:91]
	v_pk_mul_f32 v[138:139], v[88:89], v[88:89]
	s_nop 0
	v_pk_mov_b32 v[140:141], v[138:139], v[136:137] op_sel:[1,0]
	v_mov_b32_e32 v139, v137
	v_pk_add_f32 v[136:137], v[140:141], v[138:139]
	ds_read_b128 v[138:141], v129 offset:10240
	v_pk_add_f32 v[136:137], v[136:137], v[136:137] op_sel:[0,1] op_sel_hi:[1,0]
	s_waitcnt lgkmcnt(0)
	v_xor_b32_e32 v141, 0x80000000, v141
	v_xor_b32_e32 v140, 0x80000000, v140
	v_pk_fma_f32 v[86:87], v[86:87], v[130:131], v[140:141] op_sel_hi:[1,0,1]
	v_pk_fma_f32 v[84:85], v[84:85], v[130:131], v[138:139] op_sel_hi:[1,0,1] neg_lo:[0,0,1] neg_hi:[0,0,1]
	ds_read_b128 v[138:141], v129 offset:11264
	s_waitcnt lgkmcnt(0)
	v_xor_b32_e32 v141, 0x80000000, v141
	v_xor_b32_e32 v140, 0x80000000, v140
	v_pk_fma_f32 v[82:83], v[82:83], v[128:129], v[140:141] op_sel_hi:[1,0,1]
	v_pk_fma_f32 v[80:81], v[80:81], v[128:129], v[138:139] op_sel_hi:[1,0,1] neg_lo:[0,0,1] neg_hi:[0,0,1]
	ds_read_b128 v[138:141], v129 offset:12288
	s_waitcnt lgkmcnt(0)
	v_xor_b32_e32 v141, 0x80000000, v141
	v_xor_b32_e32 v140, 0x80000000, v140
	v_pk_fma_f32 v[76:77], v[76:77], v[130:131], v[138:139] op_sel_hi:[1,0,1] neg_lo:[0,0,1] neg_hi:[0,0,1]
	v_pk_fma_f32 v[78:79], v[78:79], v[130:131], v[140:141] op_sel_hi:[1,0,1]
	v_mul_f32_e32 v131, v76, v76
	v_mul_f32_e32 v140, v77, v77
	v_pk_add_f32 v[138:139], v[142:143], v[142:143] op_sel:[0,1] op_sel_hi:[1,0]
	v_mov_b32_e32 v133, v131
	v_mov_b32_e32 v139, v140
	v_pk_add_f32 v[132:133], v[132:133], v[138:139]
	v_mul_f32_e32 v138, v85, v85
	v_mul_f32_e32 v141, v78, v78
	v_pk_fma_f32 v[138:139], v[84:85], v[84:85], v[138:139] op_sel_hi:[1,1,0]
	v_mul_f32_e32 v140, v87, v87
	v_mul_f32_e32 v144, v79, v79
	v_mov_b32_e32 v139, v141
	v_pk_fma_f32 v[140:141], v[86:87], v[86:87], v[140:141] op_sel_hi:[1,1,0]
	s_nop 0
	v_mov_b32_e32 v141, v144
	v_pk_add_f32 v[138:139], v[138:139], v[140:141]
	s_nop 0
	v_pk_add_f32 v[132:133], v[132:133], v[138:139]
	ds_read_b128 v[138:141], v129 offset:13312
	v_pk_add_f32 v[132:133], v[132:133], v[132:133] op_sel:[0,1] op_sel_hi:[1,0]
	s_waitcnt lgkmcnt(0)
	v_pk_fma_f32 v[72:73], v[72:73], v[128:129], v[138:139] op_sel_hi:[1,0,1] neg_lo:[0,0,1] neg_hi:[0,0,1]
	s_nop 0
	v_mul_f32_e32 v131, v72, v72
	v_mul_f32_e32 v138, v73, v73
	v_xor_b32_e32 v141, 0x80000000, v141
	v_xor_b32_e32 v140, 0x80000000, v140
	v_mov_b32_e32 v135, v131
	v_mov_b32_e32 v137, v138
	v_pk_fma_f32 v[74:75], v[74:75], v[128:129], v[140:141] op_sel_hi:[1,0,1]
	v_pk_add_f32 v[134:135], v[134:135], v[136:137]
	v_mul_f32_e32 v136, v81, v81
	v_mul_f32_e32 v139, v74, v74
	v_pk_fma_f32 v[136:137], v[80:81], v[80:81], v[136:137] op_sel_hi:[1,1,0]
	v_mul_f32_e32 v138, v83, v83
	v_mul_f32_e32 v140, v75, v75
	v_mov_b32_e32 v137, v139
	v_pk_fma_f32 v[138:139], v[82:83], v[82:83], v[138:139] op_sel_hi:[1,1,0]
	s_nop 0
	v_mov_b32_e32 v139, v140
	v_pk_add_f32 v[136:137], v[136:137], v[138:139]
	s_nop 0
	v_pk_add_f32 v[134:135], v[134:135], v[136:137]
	ds_read_b128 v[136:139], v129 offset:14336
	v_pk_add_f32 v[134:135], v[134:135], v[134:135] op_sel:[0,1] op_sel_hi:[1,0]
	s_waitcnt lgkmcnt(0)
	v_xor_b32_e32 v139, 0x80000000, v139
	v_xor_b32_e32 v138, 0x80000000, v138
	v_pk_fma_f32 v[70:71], v[70:71], v[130:131], v[138:139] op_sel_hi:[1,0,1]
	v_pk_fma_f32 v[68:69], v[68:69], v[130:131], v[136:137] op_sel_hi:[1,0,1] neg_lo:[0,0,1] neg_hi:[0,0,1]
	v_pk_mul_f32 v[136:137], v[70:71], v[70:71]
	v_pk_mul_f32 v[138:139], v[68:69], v[68:69]
	s_nop 0
	v_pk_mov_b32 v[140:141], v[138:139], v[136:137] op_sel:[1,0]
	v_mov_b32_e32 v139, v137
	v_pk_add_f32 v[142:143], v[140:141], v[138:139]
	ds_read_b128 v[136:139], v129 offset:15360
	s_waitcnt lgkmcnt(0)
; template <int DV, int NMAP> ...
;     ...
;                 for (int qb = 0; qb < 2; ++qb) { const f32x4 x = o[db][qb] * inv[qb] - xch[(db * 2 + qb) * 64 + lane]; o[db][qb] = x; ss[qb] += (x[0] * x[0] + x[1] * x[1]) + (x[2] * x[2] + x[3] * x[3]); if (qb == 1 && (db & 1)) asm volatile("" ::: "memory"); }
	v_xor_b32_e32 v139, 0x80000000, v139
	v_xor_b32_e32 v138, 0x80000000, v138
	v_pk_fma_f32 v[66:67], v[66:67], v[128:129], v[138:139] op_sel_hi:[1,0,1]
	v_pk_fma_f32 v[64:65], v[64:65], v[128:129], v[136:137] op_sel_hi:[1,0,1] neg_lo:[0,0,1] neg_hi:[0,0,1]
	v_pk_mul_f32 v[136:137], v[66:67], v[66:67]
	v_pk_mul_f32 v[138:139], v[64:65], v[64:65]
	s_nop 0
	v_pk_mov_b32 v[140:141], v[138:139], v[136:137] op_sel:[1,0]
	v_mov_b32_e32 v139, v137
	v_pk_add_f32 v[136:137], v[140:141], v[138:139]
	ds_read_b128 v[138:141], v129 offset:16384
	v_pk_add_f32 v[136:137], v[136:137], v[136:137] op_sel:[0,1] op_sel_hi:[1,0]
	s_waitcnt lgkmcnt(0)
	v_xor_b32_e32 v141, 0x80000000, v141
	v_xor_b32_e32 v140, 0x80000000, v140
	v_pk_fma_f32 v[62:63], v[62:63], v[130:131], v[140:141] op_sel_hi:[1,0,1]
	v_pk_fma_f32 v[60:61], v[60:61], v[130:131], v[138:139] op_sel_hi:[1,0,1] neg_lo:[0,0,1] neg_hi:[0,0,1]
	ds_read_b128 v[138:141], v129 offset:17408
	s_waitcnt lgkmcnt(0)
	v_xor_b32_e32 v141, 0x80000000, v141
	v_xor_b32_e32 v140, 0x80000000, v140
	v_pk_fma_f32 v[58:59], v[58:59], v[128:129], v[140:141] op_sel_hi:[1,0,1]
	v_pk_fma_f32 v[56:57], v[56:57], v[128:129], v[138:139] op_sel_hi:[1,0,1] neg_lo:[0,0,1] neg_hi:[0,0,1]
	ds_read_b128 v[138:141], v129 offset:18432
	s_waitcnt lgkmcnt(0)
	v_xor_b32_e32 v141, 0x80000000, v141
	v_xor_b32_e32 v140, 0x80000000, v140
	v_pk_fma_f32 v[52:53], v[52:53], v[130:131], v[138:139] op_sel_hi:[1,0,1] neg_lo:[0,0,1] neg_hi:[0,0,1]
	v_pk_fma_f32 v[54:55], v[54:55], v[130:131], v[140:141] op_sel_hi:[1,0,1]
	v_mul_f32_e32 v131, v52, v52
	v_mul_f32_e32 v140, v53, v53
	v_pk_add_f32 v[138:139], v[142:143], v[142:143] op_sel:[0,1] op_sel_hi:[1,0]
	v_mov_b32_e32 v133, v131
	v_mov_b32_e32 v139, v140
	v_pk_add_f32 v[132:133], v[132:133], v[138:139]
	v_mul_f32_e32 v138, v61, v61
	v_mul_f32_e32 v141, v54, v54
	v_pk_fma_f32 v[138:139], v[60:61], v[60:61], v[138:139] op_sel_hi:[1,1,0]
	v_mul_f32_e32 v140, v63, v63
	v_mul_f32_e32 v144, v55, v55
	v_mov_b32_e32 v139, v141
	v_pk_fma_f32 v[140:141], v[62:63], v[62:63], v[140:141] op_sel_hi:[1,1,0]
	s_nop 0
	v_mov_b32_e32 v141, v144
	v_pk_add_f32 v[138:139], v[138:139], v[140:141]
	s_nop 0
	v_pk_add_f32 v[132:133], v[132:133], v[138:139]
	ds_read_b128 v[138:141], v129 offset:19456
	v_pk_add_f32 v[132:133], v[132:133], v[132:133] op_sel:[0,1] op_sel_hi:[1,0]
	s_waitcnt lgkmcnt(0)
	v_pk_fma_f32 v[48:49], v[48:49], v[128:129], v[138:139] op_sel_hi:[1,0,1] neg_lo:[0,0,1] neg_hi:[0,0,1]
	s_nop 0
	v_mul_f32_e32 v131, v48, v48
	v_mul_f32_e32 v138, v49, v49
	v_xor_b32_e32 v141, 0x80000000, v141
	v_xor_b32_e32 v140, 0x80000000, v140
	v_mov_b32_e32 v135, v131
	v_mov_b32_e32 v137, v138
	v_pk_fma_f32 v[50:51], v[50:51], v[128:129], v[140:141] op_sel_hi:[1,0,1]
	v_pk_add_f32 v[134:135], v[134:135], v[136:137]
	v_mul_f32_e32 v136, v57, v57
	v_mul_f32_e32 v139, v50, v50
	v_pk_fma_f32 v[136:137], v[56:57], v[56:57], v[136:137] op_sel_hi:[1,1,0]
	v_mul_f32_e32 v138, v59, v59
	v_mul_f32_e32 v140, v51, v51
	v_mov_b32_e32 v137, v139
	v_pk_fma_f32 v[138:139], v[58:59], v[58:59], v[138:139] op_sel_hi:[1,1,0]
	s_nop 0
	v_mov_b32_e32 v139, v140
	v_pk_add_f32 v[136:137], v[136:137], v[138:139]
	s_nop 0
	v_pk_add_f32 v[134:135], v[134:135], v[136:137]
	ds_read_b128 v[136:139], v129 offset:20480
	s_waitcnt lgkmcnt(0)
	v_xor_b32_e32 v139, 0x80000000, v139
	v_xor_b32_e32 v138, 0x80000000, v138
	v_pk_fma_f32 v[46:47], v[46:47], v[130:131], v[138:139] op_sel_hi:[1,0,1]
	v_pk_fma_f32 v[44:45], v[44:45], v[130:131], v[136:137] op_sel_hi:[1,0,1] neg_lo:[0,0,1] neg_hi:[0,0,1]
	v_pk_mul_f32 v[136:137], v[46:47], v[46:47]
	v_pk_mul_f32 v[138:139], v[44:45], v[44:45]
	s_nop 0
	v_pk_mov_b32 v[140:141], v[138:139], v[136:137] op_sel:[1,0]
	v_mov_b32_e32 v139, v137
	v_pk_add_f32 v[142:143], v[140:141], v[138:139]
	ds_read_b128 v[136:139], v129 offset:21504
	s_waitcnt lgkmcnt(0)
	v_xor_b32_e32 v139, 0x80000000, v139
	v_xor_b32_e32 v138, 0x80000000, v138
	v_pk_fma_f32 v[42:43], v[42:43], v[128:129], v[138:139] op_sel_hi:[1,0,1]
	v_pk_fma_f32 v[40:41], v[40:41], v[128:129], v[136:137] op_sel_hi:[1,0,1] neg_lo:[0,0,1] neg_hi:[0,0,1]
	v_pk_mul_f32 v[136:137], v[42:43], v[42:43]
	v_pk_mul_f32 v[138:139], v[40:41], v[40:41]
	s_nop 0
	v_pk_mov_b32 v[140:141], v[138:139], v[136:137] op_sel:[1,0]
	v_mov_b32_e32 v139, v137
	v_pk_add_f32 v[136:137], v[140:141], v[138:139]
	ds_read_b128 v[138:141], v129 offset:22528
	s_waitcnt lgkmcnt(0)
	v_xor_b32_e32 v141, 0x80000000, v141
	v_xor_b32_e32 v140, 0x80000000, v140
	v_pk_fma_f32 v[38:39], v[38:39], v[130:131], v[140:141] op_sel_hi:[1,0,1]
	v_pk_fma_f32 v[36:37], v[36:37], v[130:131], v[138:139] op_sel_hi:[1,0,1] neg_lo:[0,0,1] neg_hi:[0,0,1]
	ds_read_b128 v[138:141], v129 offset:23552
	s_waitcnt lgkmcnt(0)
	v_xor_b32_e32 v141, 0x80000000, v141
	v_xor_b32_e32 v140, 0x80000000, v140
	v_pk_fma_f32 v[34:35], v[34:35], v[128:129], v[140:141] op_sel_hi:[1,0,1]
	v_pk_fma_f32 v[32:33], v[32:33], v[128:129], v[138:139] op_sel_hi:[1,0,1] neg_lo:[0,0,1] neg_hi:[0,0,1]
	ds_read_b128 v[138:141], v129 offset:24576
	s_waitcnt lgkmcnt(0)
	v_xor_b32_e32 v141, 0x80000000, v141
	v_xor_b32_e32 v140, 0x80000000, v140
	v_pk_fma_f32 v[28:29], v[28:29], v[130:131], v[138:139] op_sel_hi:[1,0,1] neg_lo:[0,0,1] neg_hi:[0,0,1]
	v_pk_fma_f32 v[30:31], v[30:31], v[130:131], v[140:141] op_sel_hi:[1,0,1]
	v_mul_f32_e32 v131, v28, v28
	v_mul_f32_e32 v140, v29, v29
	v_pk_add_f32 v[138:139], v[142:143], v[142:143] op_sel:[0,1] op_sel_hi:[1,0]
	v_mov_b32_e32 v133, v131
	v_mov_b32_e32 v139, v140
	v_pk_add_f32 v[132:133], v[132:133], v[138:139]
	v_mul_f32_e32 v138, v37, v37
	v_mul_f32_e32 v141, v30, v30
	v_pk_fma_f32 v[138:139], v[36:37], v[36:37], v[138:139] op_sel_hi:[1,1,0]
	v_mul_f32_e32 v140, v39, v39
	v_mul_f32_e32 v144, v31, v31
	v_mov_b32_e32 v139, v141
	v_pk_fma_f32 v[140:141], v[38:39], v[38:39], v[140:141] op_sel_hi:[1,1,0]
	s_nop 0
	v_mov_b32_e32 v141, v144
	v_pk_add_f32 v[138:139], v[138:139], v[140:141]
	ds_read_b128 v[140:143], v129 offset:25600
	v_pk_add_f32 v[138:139], v[132:133], v[138:139]
	s_waitcnt lgkmcnt(0)
; template <int DV, int NMAP> ...
;     ...
;                 for (int qb = 0; qb < 2; ++qb) { const f32x4 x = o[db][qb] * inv[qb] - xch[(db * 2 + qb) * 64 + lane]; o[db][qb] = x; ss[qb] += (x[0] * x[0] + x[1] * x[1]) + (x[2] * x[2] + x[3] * x[3]); if (qb == 1 && (db & 1)) asm volatile("" ::: "memory"); }
; #pragma unroll
;             for (int qb = 0; qb < 2; ++qb) { float v = ss[qb]; v += __shfl_xor(v, 16); v += __shfl_xor(v, 32); ss[qb] = outscale / sqrtf(v * (1.0f / DV) + RMS_EPS); }
	v_xor_b32_e32 v133, 0x80000000, v143
	v_xor_b32_e32 v132, 0x80000000, v142
	v_pk_fma_f32 v[24:25], v[24:25], v[128:129], v[140:141] op_sel_hi:[1,0,1] neg_lo:[0,0,1] neg_hi:[0,0,1]
	v_pk_fma_f32 v[26:27], v[26:27], v[128:129], v[132:133] op_sel_hi:[1,0,1]
	v_mul_f32_e32 v131, v24, v24
	v_mul_f32_e32 v140, v25, v25
	v_pk_add_f32 v[132:133], v[134:135], v[134:135] op_sel:[0,1] op_sel_hi:[1,0]
	v_pk_add_f32 v[134:135], v[136:137], v[136:137] op_sel:[0,1] op_sel_hi:[1,0]
	v_mov_b32_e32 v133, v131
	v_mov_b32_e32 v135, v140
	v_pk_add_f32 v[132:133], v[132:133], v[134:135]
	v_mul_f32_e32 v134, v33, v33
	v_mul_f32_e32 v136, v35, v35
	v_mul_f32_e32 v141, v26, v26
	v_mul_f32_e32 v142, v27, v27
	v_pk_fma_f32 v[134:135], v[32:33], v[32:33], v[134:135] op_sel_hi:[1,1,0]
	v_pk_fma_f32 v[136:137], v[34:35], v[34:35], v[136:137] op_sel_hi:[1,1,0]
	v_mov_b32_e32 v135, v141
	v_mov_b32_e32 v137, v142
	v_pk_add_f32 v[134:135], v[134:135], v[136:137]
	s_nop 0
	v_pk_add_f32 v[136:137], v[132:133], v[134:135]
	ds_read_b128 v[132:135], v129 offset:26624
	s_waitcnt lgkmcnt(0)
	v_xor_b32_e32 v135, 0x80000000, v135
	v_xor_b32_e32 v134, 0x80000000, v134
	v_pk_fma_f32 v[22:23], v[22:23], v[130:131], v[134:135] op_sel_hi:[1,0,1]
	v_pk_fma_f32 v[20:21], v[20:21], v[130:131], v[132:133] op_sel_hi:[1,0,1] neg_lo:[0,0,1] neg_hi:[0,0,1]
	v_pk_mul_f32 v[132:133], v[22:23], v[22:23]
	v_pk_mul_f32 v[134:135], v[20:21], v[20:21]
	s_nop 0
	v_pk_mov_b32 v[140:141], v[134:135], v[132:133] op_sel:[1,0]
	v_mov_b32_e32 v135, v133
	v_pk_add_f32 v[146:147], v[140:141], v[134:135]
	ds_read_b128 v[140:143], v129 offset:27648
	s_waitcnt lgkmcnt(0)
	v_xor_b32_e32 v133, 0x80000000, v143
	v_xor_b32_e32 v132, 0x80000000, v142
	ds_read_b128 v[142:145], v129 offset:28672
	v_pk_fma_f32 v[132:133], v[14:15], v[128:129], v[132:133] op_sel_hi:[1,0,1]
	v_pk_fma_f32 v[134:135], v[12:13], v[128:129], v[140:141] op_sel_hi:[1,0,1] neg_lo:[0,0,1] neg_hi:[0,0,1]
	v_pk_mul_f32 v[12:13], v[132:133], v[132:133]
	v_pk_mul_f32 v[14:15], v[134:135], v[134:135]
	s_nop 0
	v_pk_mov_b32 v[140:141], v[14:15], v[12:13] op_sel:[1,0]
	v_mov_b32_e32 v15, v13
	s_waitcnt lgkmcnt(0)
	v_xor_b32_e32 v13, 0x80000000, v145
	v_xor_b32_e32 v12, 0x80000000, v144
	v_pk_add_f32 v[140:141], v[140:141], v[14:15]
	v_pk_fma_f32 v[12:13], v[18:19], v[130:131], v[12:13] op_sel_hi:[1,0,1]
	v_pk_fma_f32 v[14:15], v[16:17], v[130:131], v[142:143] op_sel_hi:[1,0,1] neg_lo:[0,0,1] neg_hi:[0,0,1]
	ds_read_b128 v[16:19], v129 offset:29696
	s_waitcnt lgkmcnt(0)
	v_xor_b32_e32 v19, 0x80000000, v19
	v_xor_b32_e32 v18, 0x80000000, v18
	v_pk_fma_f32 v[10:11], v[10:11], v[128:129], v[18:19] op_sel_hi:[1,0,1]
	v_pk_fma_f32 v[8:9], v[8:9], v[128:129], v[16:17] op_sel_hi:[1,0,1] neg_lo:[0,0,1] neg_hi:[0,0,1]
	ds_read_b128 v[16:19], v129 offset:30720
	s_waitcnt lgkmcnt(0)
	v_xor_b32_e32 v19, 0x80000000, v19
	v_xor_b32_e32 v18, 0x80000000, v18
	v_pk_fma_f32 v[4:5], v[4:5], v[130:131], v[16:17] op_sel_hi:[1,0,1] neg_lo:[0,0,1] neg_hi:[0,0,1]
	v_pk_fma_f32 v[6:7], v[6:7], v[130:131], v[18:19] op_sel_hi:[1,0,1]
	v_mul_f32_e32 v18, v4, v4
	v_pk_add_f32 v[16:17], v[138:139], v[138:139] op_sel:[0,1] op_sel_hi:[1,0]
	v_mul_f32_e32 v130, v5, v5
	v_mov_b32_e32 v17, v18
	v_pk_add_f32 v[18:19], v[146:147], v[146:147] op_sel:[0,1] op_sel_hi:[1,0]
	v_mul_f32_e32 v131, v6, v6
	v_mov_b32_e32 v19, v130
	v_pk_add_f32 v[16:17], v[16:17], v[18:19]
	v_mul_f32_e32 v18, v15, v15
	v_pk_fma_f32 v[18:19], v[14:15], v[14:15], v[18:19] op_sel_hi:[1,1,0]
	v_mul_f32_e32 v130, v13, v13
	v_mul_f32_e32 v142, v7, v7
	v_mov_b32_e32 v19, v131
	v_pk_fma_f32 v[130:131], v[12:13], v[12:13], v[130:131] op_sel_hi:[1,1,0]
	s_nop 0
	v_mov_b32_e32 v131, v142
	ds_read_b128 v[142:145], v129 offset:31744
	v_pk_add_f32 v[18:19], v[18:19], v[130:131]
	s_nop 0
	v_pk_add_f32 v[16:17], v[16:17], v[18:19]
	s_waitcnt lgkmcnt(0)
	v_pk_fma_f32 v[18:19], v[0:1], v[128:129], v[142:143] op_sel_hi:[1,0,1] neg_lo:[0,0,1] neg_hi:[0,0,1]
	v_add_f32_e32 v130, v16, v17
	v_xor_b32_e32 v17, 0x80000000, v145
	v_xor_b32_e32 v16, 0x80000000, v144
	v_pk_fma_f32 v[16:17], v[2:3], v[128:129], v[16:17] op_sel_hi:[1,0,1]
	v_mul_f32_e32 v2, v18, v18
	v_pk_add_f32 v[0:1], v[136:137], v[136:137] op_sel:[0,1] op_sel_hi:[1,0]
	v_mul_f32_e32 v128, v19, v19
	v_mov_b32_e32 v1, v2
	v_pk_add_f32 v[2:3], v[140:141], v[140:141] op_sel:[0,1] op_sel_hi:[1,0]
	v_mul_f32_e32 v129, v16, v16
	v_mov_b32_e32 v3, v128
	v_pk_add_f32 v[0:1], v[0:1], v[2:3]
	v_mul_f32_e32 v2, v9, v9
	v_pk_fma_f32 v[2:3], v[8:9], v[8:9], v[2:3] op_sel_hi:[1,1,0]
	v_mul_f32_e32 v128, v11, v11
	v_mul_f32_e32 v131, v17, v17
	v_mov_b32_e32 v3, v129
	v_pk_fma_f32 v[128:129], v[10:11], v[10:11], v[128:129] op_sel_hi:[1,1,0]
	s_nop 0
	v_mov_b32_e32 v129, v131
	v_pk_add_f32 v[2:3], v[2:3], v[128:129]
	s_nop 0
	v_pk_add_f32 v[0:1], v[0:1], v[2:3]
	s_nop 0
	v_add_f32_e32 v0, v0, v1
	ds_bpermute_b32 v1, v231, v130
	s_waitcnt lgkmcnt(0)
	v_add_f32_e32 v1, v130, v1
	ds_bpermute_b32 v2, v232, v1
	s_waitcnt lgkmcnt(0)
	v_add_f32_e32 v1, v1, v2
	v_fmamk_f32 v1, v1, 0x3b800000, v226
	v_cmp_gt_f32_e32 vcc, s93, v1
	v_mul_f32_e32 v2, 0x4f800000, v1
	s_nop 0
	v_cndmask_b32_e32 v1, v1, v2, vcc
	v_sqrt_f32_e32 v2, v1
	s_nop 0
	v_add_u32_e32 v3, -1, v2
	v_fma_f32 v128, -v3, v2, v1
	v_cmp_ge_f32_e64 s[38:39], 0, v128
	v_add_u32_e32 v128, 1, v2
	s_nop 0
	v_cndmask_b32_e64 v3, v2, v3, s[38:39]
	v_fma_f32 v2, -v128, v2, v1
	v_cmp_lt_f32_e64 s[38:39], 0, v2
	s_nop 1
	v_cndmask_b32_e64 v2, v3, v128, s[38:39]
	v_mul_f32_e32 v3, 0x37800000, v2
	v_cndmask_b32_e32 v2, v2, v3, vcc
	v_cmp_class_f32_e32 vcc, v1, v227
	s_nop 1
	v_cndmask_b32_e32 v1, v2, v1, vcc
	v_div_scale_f32 v2, s[4:5], v1, v1, v234
	v_rcp_f32_e32 v3, v2
	s_nop 0
	v_fma_f32 v128, -v2, v3, 1.0
	v_fmac_f32_e32 v3, v128, v3
	v_div_scale_f32 v128, vcc, v234, v1, v234
	v_mul_f32_e32 v129, v128, v3
	v_fma_f32 v130, -v2, v129, v128
	v_fmac_f32_e32 v129, v130, v3
	v_fma_f32 v2, -v2, v129, v128
	v_div_fmas_f32 v2, v2, v3, v129
	v_div_fixup_f32 v130, v2, v1, v234
	ds_bpermute_b32 v1, v231, v0
	s_waitcnt lgkmcnt(0)
; __device__ __forceinline__ unsigned cvt_pk_bf16(float lo, float hi) { unsigned r; asm volatile("v_cvt_pk_bf16_f32 %0, %1, %2" : "=v"(r) : "v"(lo), "v"(hi)); return r; }
; template <int DV, int NMAP> ...
;     ...
;             for (int qb = 0; qb < 2; ++qb) { float v = ss[qb]; v += __shfl_xor(v, 16); v += __shfl_xor(v, 32); ss[qb] = outscale / sqrtf(v * (1.0f / DV) + RMS_EPS); }
; #pragma unroll
;             for (int db = 0; db < DV / 16; ++db) { const f32x4 g = *(const f32x4*)(subg + 16 * db + 4 * fq);
; #pragma unroll
;                 for (int qb = 0; qb < 2; ++qb) { const f32x4 v = o[db][qb] * g * ss[qb]; v2u w; w.x = pg8::cvt_pk_bf16(v[0], v[1]); w.y = pg8::cvt_pk_bf16(v[2], v[3]);
;                     *(v2u*)(O + (size_t)(q0w + 16 * qb + fr) * DM + vrow0 + 16 * db + 4 * fq) = w; } }
	v_add_f32_e32 v0, v0, v1
	ds_bpermute_b32 v1, v232, v0
	s_waitcnt lgkmcnt(0)
	v_add_f32_e32 v0, v0, v1
	v_fmamk_f32 v0, v0, 0x3b800000, v226
	v_cmp_gt_f32_e32 vcc, s93, v0
	v_mul_f32_e32 v1, 0x4f800000, v0
	s_nop 0
	v_cndmask_b32_e32 v0, v0, v1, vcc
	v_sqrt_f32_e32 v1, v0
	s_nop 0
	v_add_u32_e32 v2, -1, v1
	v_fma_f32 v3, -v2, v1, v0
	v_cmp_ge_f32_e64 s[38:39], 0, v3
	v_add_u32_e32 v3, 1, v1
	s_nop 0
	v_cndmask_b32_e64 v2, v1, v2, s[38:39]
	v_fma_f32 v1, -v3, v1, v0
	v_cmp_lt_f32_e64 s[38:39], 0, v1
	s_nop 1
	v_cndmask_b32_e64 v1, v2, v3, s[38:39]
	v_mul_f32_e32 v2, 0x37800000, v1
	v_cndmask_b32_e32 v1, v1, v2, vcc
	v_cmp_class_f32_e32 vcc, v0, v227
	s_nop 1
	v_cndmask_b32_e32 v0, v1, v0, vcc
	v_div_scale_f32 v1, s[4:5], v0, v0, v234
	v_rcp_f32_e32 v2, v1
	s_lshl_b32 s4, s36, 1
	s_add_u32 s4, s98, s4
	s_addc_u32 s5, s99, 0
	v_fma_f32 v3, -v1, v2, 1.0
	v_fmac_f32_e32 v2, v3, v2
	v_div_scale_f32 v3, vcc, v234, v0, v234
	v_mul_f32_e32 v128, v3, v2
	v_fma_f32 v129, -v1, v128, v3
	v_fmac_f32_e32 v128, v129, v2
	v_fma_f32 v1, -v1, v128, v3
	v_div_fmas_f32 v1, v1, v2, v128
	v_lshlrev_b32_e32 v129, 4, v236
	v_div_fixup_f32 v128, v1, v0, v234
	v_lshl_add_u64 v[136:137], s[4:5], 0, v[204:205]
	v_lshlrev_b32_e32 v204, 12, v235
	s_waitcnt vmcnt(0)
	v_pk_mul_f32 v[124:125], v[124:125], v[162:163]
	v_pk_mul_f32 v[126:127], v[126:127], v[160:161]
	v_pk_mul_f32 v[124:125], v[124:125], v[130:131] op_sel_hi:[1, 0]
	v_pk_mul_f32 v[126:127], v[126:127], v[130:131] op_sel_hi:[1, 0]
	v_pk_mul_f32 v[0:1], v[120:121], v[160:161]
	v_cvt_pk_bf16_f32 v126, v126, v127
	v_cvt_pk_bf16_f32 v127, v124, v125
	v_lshl_add_u64 v[124:125], v[136:137], 0, v[204:205]
	v_pk_mul_f32 v[2:3], v[122:123], v[162:163]
	v_pk_mul_f32 v[0:1], v[0:1], v[128:129] op_sel_hi:[1, 0]
	v_or_b32_e32 v204, 0x10000, v204
	global_store_dwordx2 v[124:125], v[126:127], off
	v_pk_mul_f32 v[2:3], v[2:3], v[128:129] op_sel_hi:[1, 0]
	v_cvt_pk_bf16_f32 v120, v0, v1
	v_lshl_add_u64 v[0:1], v[136:137], 0, v[204:205]
	v_cvt_pk_bf16_f32 v121, v2, v3
	global_store_dwordx2 v[0:1], v[120:121], off
	v_pk_mul_f32 v[2:3], v[118:119], v[166:167]
	v_pk_mul_f32 v[116:117], v[116:117], v[164:165]
	v_pk_mul_f32 v[2:3], v[2:3], v[130:131] op_sel_hi:[1, 0]
	v_pk_mul_f32 v[116:117], v[116:117], v[130:131] op_sel_hi:[1, 0]
	v_pk_mul_f32 v[112:113], v[112:113], v[164:165]
	v_cvt_pk_bf16_f32 v116, v116, v117
	v_cvt_pk_bf16_f32 v117, v2, v3
	v_pk_mul_f32 v[2:3], v[114:115], v[166:167]
	v_pk_mul_f32 v[112:113], v[112:113], v[128:129] op_sel_hi:[1, 0]
	global_store_dwordx2 v[124:125], v[116:117], off offset:32
	v_pk_mul_f32 v[2:3], v[2:3], v[128:129] op_sel_hi:[1, 0]
	v_cvt_pk_bf16_f32 v112, v112, v113
	s_nop 0
	v_cvt_pk_bf16_f32 v113, v2, v3
	global_store_dwordx2 v[0:1], v[112:113], off offset:32
	v_pk_mul_f32 v[2:3], v[110:111], v[170:171]
	v_pk_mul_f32 v[108:109], v[108:109], v[168:169]
	v_pk_mul_f32 v[2:3], v[130:131], v[2:3] op_sel_hi:[0, 1]
	v_pk_mul_f32 v[108:109], v[130:131], v[108:109] op_sel_hi:[0, 1]
	v_pk_mul_f32 v[104:105], v[104:105], v[168:169]
	v_cvt_pk_bf16_f32 v108, v108, v109
	v_cvt_pk_bf16_f32 v109, v2, v3
	v_pk_mul_f32 v[2:3], v[106:107], v[170:171]
	v_pk_mul_f32 v[104:105], v[128:129], v[104:105] op_sel_hi:[0, 1]
	global_store_dwordx2 v[124:125], v[108:109], off offset:64
	v_pk_mul_f32 v[2:3], v[128:129], v[2:3] op_sel_hi:[0, 1]
	v_cvt_pk_bf16_f32 v104, v104, v105
	v_cvt_pk_bf16_f32 v105, v2, v3
	global_store_dwordx2 v[0:1], v[104:105], off offset:64
	v_pk_mul_f32 v[2:3], v[102:103], v[174:175]
	v_pk_mul_f32 v[100:101], v[100:101], v[172:173]
	v_pk_mul_f32 v[2:3], v[130:131], v[2:3] op_sel_hi:[0, 1]
	v_pk_mul_f32 v[100:101], v[130:131], v[100:101] op_sel_hi:[0, 1]
	v_pk_mul_f32 v[96:97], v[96:97], v[172:173]
	v_cvt_pk_bf16_f32 v100, v100, v101
	v_cvt_pk_bf16_f32 v101, v2, v3
	v_pk_mul_f32 v[2:3], v[98:99], v[174:175]
	v_pk_mul_f32 v[96:97], v[128:129], v[96:97] op_sel_hi:[0, 1]
	global_store_dwordx2 v[124:125], v[100:101], off offset:96
	v_pk_mul_f32 v[2:3], v[128:129], v[2:3] op_sel_hi:[0, 1]
	v_cvt_pk_bf16_f32 v96, v96, v97
	v_cvt_pk_bf16_f32 v97, v2, v3
	global_store_dwordx2 v[0:1], v[96:97], off offset:96
	v_pk_mul_f32 v[2:3], v[94:95], v[178:179]
	v_pk_mul_f32 v[92:93], v[92:93], v[176:177]
	v_pk_mul_f32 v[2:3], v[130:131], v[2:3] op_sel_hi:[0, 1]
	v_pk_mul_f32 v[92:93], v[130:131], v[92:93] op_sel_hi:[0, 1]
	v_pk_mul_f32 v[88:89], v[88:89], v[176:177]
	v_cvt_pk_bf16_f32 v92, v92, v93
	v_cvt_pk_bf16_f32 v93, v2, v3
	v_pk_mul_f32 v[2:3], v[90:91], v[178:179]
	v_pk_mul_f32 v[88:89], v[128:129], v[88:89] op_sel_hi:[0, 1]
	global_store_dwordx2 v[124:125], v[92:93], off offset:128
	v_pk_mul_f32 v[2:3], v[128:129], v[2:3] op_sel_hi:[0, 1]
	v_cvt_pk_bf16_f32 v88, v88, v89
	v_cvt_pk_bf16_f32 v89, v2, v3
	global_store_dwordx2 v[0:1], v[88:89], off offset:128
	v_pk_mul_f32 v[2:3], v[86:87], v[182:183]
	v_pk_mul_f32 v[84:85], v[84:85], v[180:181]
	v_pk_mul_f32 v[2:3], v[130:131], v[2:3] op_sel_hi:[0, 1]
	v_pk_mul_f32 v[84:85], v[130:131], v[84:85] op_sel_hi:[0, 1]
	v_pk_mul_f32 v[80:81], v[80:81], v[180:181]
	v_cvt_pk_bf16_f32 v84, v84, v85
	v_cvt_pk_bf16_f32 v85, v2, v3
	v_pk_mul_f32 v[2:3], v[82:83], v[182:183]
	v_pk_mul_f32 v[80:81], v[128:129], v[80:81] op_sel_hi:[0, 1]
	global_store_dwordx2 v[124:125], v[84:85], off offset:160
	v_pk_mul_f32 v[2:3], v[128:129], v[2:3] op_sel_hi:[0, 1]
	v_cvt_pk_bf16_f32 v80, v80, v81
	v_cvt_pk_bf16_f32 v81, v2, v3
	global_store_dwordx2 v[0:1], v[80:81], off offset:160
	v_pk_mul_f32 v[2:3], v[78:79], v[186:187]
	v_pk_mul_f32 v[76:77], v[76:77], v[184:185]
	v_pk_mul_f32 v[2:3], v[130:131], v[2:3] op_sel_hi:[0, 1]
	v_pk_mul_f32 v[76:77], v[130:131], v[76:77] op_sel_hi:[0, 1]
; __device__ __forceinline__ unsigned cvt_pk_bf16(float lo, float hi) { unsigned r; asm volatile("v_cvt_pk_bf16_f32 %0, %1, %2" : "=v"(r) : "v"(lo), "v"(hi)); return r; }
; template <int DV, int NMAP> ...
;     ...
;             for (int db = 0; db < DV / 16; ++db) { const f32x4 g = *(const f32x4*)(subg + 16 * db + 4 * fq);
; #pragma unroll
;                 for (int qb = 0; qb < 2; ++qb) { const f32x4 v = o[db][qb] * g * ss[qb]; v2u w; w.x = pg8::cvt_pk_bf16(v[0], v[1]); w.y = pg8::cvt_pk_bf16(v[2], v[3]);
;                     *(v2u*)(O + (size_t)(q0w + 16 * qb + fr) * DM + vrow0 + 16 * db + 4 * fq) = w; } }
	v_pk_mul_f32 v[72:73], v[72:73], v[184:185]
	v_cvt_pk_bf16_f32 v76, v76, v77
	v_cvt_pk_bf16_f32 v77, v2, v3
	v_pk_mul_f32 v[2:3], v[74:75], v[186:187]
	v_pk_mul_f32 v[72:73], v[128:129], v[72:73] op_sel_hi:[0, 1]
	global_store_dwordx2 v[124:125], v[76:77], off offset:192
	v_pk_mul_f32 v[2:3], v[128:129], v[2:3] op_sel_hi:[0, 1]
	v_cvt_pk_bf16_f32 v72, v72, v73
	v_cvt_pk_bf16_f32 v73, v2, v3
	global_store_dwordx2 v[0:1], v[72:73], off offset:192
	v_pk_mul_f32 v[2:3], v[70:71], v[190:191]
	v_pk_mul_f32 v[68:69], v[68:69], v[188:189]
	v_pk_mul_f32 v[2:3], v[130:131], v[2:3] op_sel_hi:[0, 1]
	v_pk_mul_f32 v[68:69], v[130:131], v[68:69] op_sel_hi:[0, 1]
	v_pk_mul_f32 v[64:65], v[64:65], v[188:189]
	v_cvt_pk_bf16_f32 v68, v68, v69
	v_cvt_pk_bf16_f32 v69, v2, v3
	v_pk_mul_f32 v[2:3], v[66:67], v[190:191]
	v_pk_mul_f32 v[64:65], v[128:129], v[64:65] op_sel_hi:[0, 1]
	global_store_dwordx2 v[124:125], v[68:69], off offset:224
	v_pk_mul_f32 v[2:3], v[128:129], v[2:3] op_sel_hi:[0, 1]
	v_cvt_pk_bf16_f32 v64, v64, v65
	v_cvt_pk_bf16_f32 v65, v2, v3
	global_store_dwordx2 v[0:1], v[64:65], off offset:224
	v_pk_mul_f32 v[2:3], v[62:63], v[194:195]
	v_pk_mul_f32 v[60:61], v[60:61], v[192:193]
	v_pk_mul_f32 v[2:3], v[130:131], v[2:3] op_sel_hi:[0, 1]
	v_pk_mul_f32 v[60:61], v[130:131], v[60:61] op_sel_hi:[0, 1]
	v_pk_mul_f32 v[56:57], v[56:57], v[192:193]
	v_cvt_pk_bf16_f32 v60, v60, v61
	v_cvt_pk_bf16_f32 v61, v2, v3
	v_pk_mul_f32 v[2:3], v[58:59], v[194:195]
	v_pk_mul_f32 v[56:57], v[128:129], v[56:57] op_sel_hi:[0, 1]
	global_store_dwordx2 v[124:125], v[60:61], off offset:256
	v_pk_mul_f32 v[2:3], v[128:129], v[2:3] op_sel_hi:[0, 1]
	v_cvt_pk_bf16_f32 v56, v56, v57
	v_cvt_pk_bf16_f32 v57, v2, v3
	global_store_dwordx2 v[0:1], v[56:57], off offset:256
	v_pk_mul_f32 v[2:3], v[54:55], v[198:199]
	v_pk_mul_f32 v[52:53], v[52:53], v[196:197]
	v_pk_mul_f32 v[2:3], v[130:131], v[2:3] op_sel_hi:[0, 1]
	v_pk_mul_f32 v[52:53], v[130:131], v[52:53] op_sel_hi:[0, 1]
	v_pk_mul_f32 v[48:49], v[48:49], v[196:197]
	v_cvt_pk_bf16_f32 v52, v52, v53
	v_cvt_pk_bf16_f32 v53, v2, v3
	v_pk_mul_f32 v[2:3], v[50:51], v[198:199]
	v_pk_mul_f32 v[48:49], v[128:129], v[48:49] op_sel_hi:[0, 1]
	global_store_dwordx2 v[124:125], v[52:53], off offset:288
	v_pk_mul_f32 v[2:3], v[128:129], v[2:3] op_sel_hi:[0, 1]
	v_cvt_pk_bf16_f32 v48, v48, v49
	v_cvt_pk_bf16_f32 v49, v2, v3
	global_store_dwordx2 v[0:1], v[48:49], off offset:288
	v_pk_mul_f32 v[2:3], v[46:47], v[202:203]
	v_pk_mul_f32 v[44:45], v[44:45], v[200:201]
	v_pk_mul_f32 v[2:3], v[130:131], v[2:3] op_sel_hi:[0, 1]
	v_pk_mul_f32 v[44:45], v[130:131], v[44:45] op_sel_hi:[0, 1]
	v_pk_mul_f32 v[40:41], v[40:41], v[200:201]
	v_cvt_pk_bf16_f32 v44, v44, v45
	v_cvt_pk_bf16_f32 v45, v2, v3
	v_pk_mul_f32 v[2:3], v[42:43], v[202:203]
	v_pk_mul_f32 v[40:41], v[128:129], v[40:41] op_sel_hi:[0, 1]
	global_store_dwordx2 v[124:125], v[44:45], off offset:320
	v_pk_mul_f32 v[2:3], v[128:129], v[2:3] op_sel_hi:[0, 1]
	v_cvt_pk_bf16_f32 v40, v40, v41
	v_cvt_pk_bf16_f32 v41, v2, v3
	global_store_dwordx2 v[0:1], v[40:41], off offset:320
	v_pk_mul_f32 v[2:3], v[38:39], v[150:151]
	v_pk_mul_f32 v[36:37], v[36:37], v[148:149]
	v_pk_mul_f32 v[2:3], v[130:131], v[2:3] op_sel_hi:[0, 1]
	v_pk_mul_f32 v[36:37], v[130:131], v[36:37] op_sel_hi:[0, 1]
	v_pk_mul_f32 v[32:33], v[32:33], v[148:149]
	v_cvt_pk_bf16_f32 v36, v36, v37
	v_cvt_pk_bf16_f32 v37, v2, v3
	v_pk_mul_f32 v[2:3], v[34:35], v[150:151]
	v_pk_mul_f32 v[32:33], v[128:129], v[32:33] op_sel_hi:[0, 1]
	global_store_dwordx2 v[124:125], v[36:37], off offset:352
	v_pk_mul_f32 v[2:3], v[128:129], v[2:3] op_sel_hi:[0, 1]
	v_cvt_pk_bf16_f32 v32, v32, v33
	v_cvt_pk_bf16_f32 v33, v2, v3
	global_store_dwordx2 v[0:1], v[32:33], off offset:352
	v_pk_mul_f32 v[2:3], v[30:31], v[154:155]
	v_pk_mul_f32 v[28:29], v[28:29], v[152:153]
	v_pk_mul_f32 v[2:3], v[130:131], v[2:3] op_sel_hi:[0, 1]
	v_pk_mul_f32 v[28:29], v[130:131], v[28:29] op_sel_hi:[0, 1]
	v_pk_mul_f32 v[24:25], v[24:25], v[152:153]
	v_cvt_pk_bf16_f32 v28, v28, v29
	v_cvt_pk_bf16_f32 v29, v2, v3
	v_pk_mul_f32 v[2:3], v[26:27], v[154:155]
	v_pk_mul_f32 v[24:25], v[128:129], v[24:25] op_sel_hi:[0, 1]
	global_store_dwordx2 v[124:125], v[28:29], off offset:384
	v_pk_mul_f32 v[2:3], v[128:129], v[2:3] op_sel_hi:[0, 1]
	v_cvt_pk_bf16_f32 v24, v24, v25
	v_cvt_pk_bf16_f32 v25, v2, v3
	global_store_dwordx2 v[0:1], v[24:25], off offset:384
	v_pk_mul_f32 v[20:21], v[20:21], v[240:241]
	v_pk_mul_f32 v[2:3], v[22:23], v[242:243]
	v_pk_mul_f32 v[20:21], v[130:131], v[20:21] op_sel_hi:[0, 1]
	v_pk_mul_f32 v[2:3], v[130:131], v[2:3] op_sel_hi:[0, 1]
	v_cvt_pk_bf16_f32 v20, v20, v21
	v_cvt_pk_bf16_f32 v21, v2, v3
	global_store_dwordx2 v[124:125], v[20:21], off offset:416
	v_pk_mul_f32 v[20:21], v[134:135], v[240:241]
	v_pk_mul_f32 v[2:3], v[132:133], v[242:243]
	v_pk_mul_f32 v[20:21], v[128:129], v[20:21] op_sel_hi:[0, 1]
	v_pk_mul_f32 v[2:3], v[128:129], v[2:3] op_sel_hi:[0, 1]
	v_cvt_pk_bf16_f32 v20, v20, v21
	v_cvt_pk_bf16_f32 v21, v2, v3
	global_store_dwordx2 v[0:1], v[20:21], off offset:416
	v_pk_mul_f32 v[2:3], v[12:13], v[246:247]
	v_pk_mul_f32 v[12:13], v[14:15], v[244:245]
	v_pk_mul_f32 v[2:3], v[130:131], v[2:3] op_sel_hi:[0, 1]
	v_pk_mul_f32 v[12:13], v[130:131], v[12:13] op_sel_hi:[0, 1]
	v_pk_mul_f32 v[8:9], v[8:9], v[244:245]
	v_cvt_pk_bf16_f32 v12, v12, v13
	v_cvt_pk_bf16_f32 v13, v2, v3
	v_pk_mul_f32 v[2:3], v[10:11], v[246:247]
	v_pk_mul_f32 v[8:9], v[128:129], v[8:9] op_sel_hi:[0, 1]
	global_store_dwordx2 v[124:125], v[12:13], off offset:448
	v_pk_mul_f32 v[2:3], v[128:129], v[2:3] op_sel_hi:[0, 1]
	v_cvt_pk_bf16_f32 v8, v8, v9
	v_cvt_pk_bf16_f32 v9, v2, v3
	global_store_dwordx2 v[0:1], v[8:9], off offset:448
	v_pk_mul_f32 v[4:5], v[4:5], v[248:249]
	v_pk_mul_f32 v[2:3], v[6:7], v[250:251]
	v_pk_mul_f32 v[4:5], v[130:131], v[4:5] op_sel_hi:[0, 1]
	v_pk_mul_f32 v[2:3], v[130:131], v[2:3] op_sel_hi:[0, 1]
	v_cvt_pk_bf16_f32 v4, v4, v5
	v_cvt_pk_bf16_f32 v5, v2, v3
	global_store_dwordx2 v[124:125], v[4:5], off offset:480
	v_pk_mul_f32 v[4:5], v[18:19], v[248:249]
	v_pk_mul_f32 v[2:3], v[16:17], v[250:251]
	v_pk_mul_f32 v[4:5], v[128:129], v[4:5] op_sel_hi:[0, 1]
	v_pk_mul_f32 v[2:3], v[128:129], v[2:3] op_sel_hi:[0, 1]
	v_cvt_pk_bf16_f32 v4, v4, v5
	v_cvt_pk_bf16_f32 v5, v2, v3
	global_store_dwordx2 v[0:1], v[4:5], off offset:480
	s_branch .LBB0_297
